# P4 gate-up epilogue: dropped store-ack waits (vmcnt(0) in conv blocks 1-3, tile-top vmcnt(1) replaced by a wait on the rare skip path)
# speedup vs baseline: 1.0118x; 1.0118x over previous
.LBB0_20:
	s_ashr_i32 s15, s90, 5
	s_and_b32 s5, s90, 7
	s_and_b32 s14, s15, -8
	s_or_b32 s14, s14, s5
	s_lshr_b32 s5, s15, 30
	s_add_i32 s5, s14, s5
	s_and_b32 s15, s5, -4
	s_bfe_u32 s19, s90, 0x20006
	s_or_b32 s91, s15, s19
	s_cmpk_gt_i32 s91, 0x142
	s_cbranch_scc1 .LBB0_19
	v_mov_b32_e32 v14, v171
	s_ashr_i32 s15, s5, 2
	v_ashrrev_i32_e32 v1, 31, v14
	v_lshrrev_b32_e32 v1, 26, v1
	v_add_u32_e32 v1, v14, v1
	v_ashrrev_i32_e32 v8, 6, v1
	v_bfe_i32 v1, v14, 27, 1
	v_lshlrev_b32_e32 v0, 4, v14
	v_lshrrev_b32_e32 v1, 22, v1
	v_add_u32_e32 v1, v0, v1
	v_and_b32_e32 v1, 0xfffffc00, v1
	v_sub_u32_e32 v1, v0, v1
	v_lshrrev_b32_e32 v2, 4, v1
	v_bitop3_b32 v1, v2, v1, 32 bitop3:0x6c
	v_ashrrev_i32_e32 v3, 31, v1
	v_lshrrev_b32_e32 v3, 26, v3
	v_add_u32_e32 v3, v1, v3
	v_ashrrev_i32_e32 v10, 6, v3
	v_and_b32_e32 v3, 0xc0, v3
	v_sub_u32_e32 v1, v1, v3
	v_lshlrev_b32_e32 v2, 3, v8
	v_lshlrev_b32_e32 v4, 5, v8
	v_ashrrev_i16_sdwa v1, v177, sext(v1) dst_sel:DWORD dst_unused:UNUSED_PAD src0_sel:DWORD src1_sel:BYTE_0
	v_and_b32_e32 v2, 0x1ffff0, v2
	v_and_b32_e32 v4, 32, v4
	v_bfe_i32 v11, v1, 0, 16
	v_add_u32_e32 v1, v4, v11
	v_add_lshl_u32 v2, v10, v2, 11
	v_add_u32_e32 v0, 0x2000, v0
	v_lshl_add_u32 v168, v1, 1, v2
	v_ashrrev_i32_e32 v1, 31, v0
	v_lshrrev_b32_e32 v1, 22, v1
	v_add_u32_e32 v1, v0, v1
	v_ashrrev_i32_e32 v9, 10, v1
	v_mul_i32_i24_e32 v1, 0x400, v9
	v_sub_u32_e32 v0, v0, v1
	v_lshrrev_b32_e32 v1, 4, v0
	s_lshl_b32 s5, s15, 2
	v_bitop3_b32 v0, v1, v0, 32 bitop3:0x6c
	s_sub_i32 s5, s14, s5
	v_ashrrev_i32_e32 v2, 31, v0
	s_lshl_b32 s5, s5, 3
	s_bfe_u32 s19, s90, 0x30003
	s_mulk_i32 s91, 0xfe
	v_lshrrev_b32_e32 v2, 26, v2
	s_or_b32 s40, s5, s19
	s_add_i32 s58, s91, -1
	v_readfirstlane_b32 s92, v14
	v_add_u32_e32 v2, v0, v2
	s_ashr_i32 s59, s58, 31
	s_ashr_i32 s5, s92, 6
	v_ashrrev_i32_e32 v12, 6, v2
	v_and_b32_e32 v2, 0xc0, v2
	s_ashr_i32 s41, s40, 31
	v_sub_u32_e32 v0, v0, v2
	s_ashr_i32 s93, s92, 8
	s_lshl_b32 s94, s5, 10
	s_lshl_b64 s[26:27], s[58:59], 11
	s_lshl_b64 s[28:29], s[40:41], 19
	v_readlane_b32 s19, v255, 10
	v_lshlrev_b32_e32 v1, 3, v9
	v_lshlrev_b32_e32 v3, 5, v9
	v_ashrrev_i16_sdwa v0, v177, sext(v0) dst_sel:DWORD dst_unused:UNUSED_PAD src0_sel:DWORD src1_sel:BYTE_0
	s_add_u32 s84, s19, s28
	v_readlane_b32 s19, v255, 6
	v_and_b32_e32 v1, 0x1ffff0, v1
	v_and_b32_e32 v3, 32, v3
	v_bfe_i32 v13, v0, 0, 16
	s_addc_u32 s85, s19, s29
	s_add_i32 s41, s94, 0x10000
	s_add_i32 s59, s94, 0x12000
	v_add_u32_e32 v0, v3, v13
	v_add_lshl_u32 v1, v12, v1, 11
	s_mov_b32 m0, s41
	s_add_u32 s28, s84, 0x40000
	v_lshl_add_u32 v128, v0, 1, v1
	global_load_lds_dwordx4 v168, s[84:85]
	s_mov_b32 m0, s59
	s_addc_u32 s29, s85, 0
	s_add_i32 s95, s94, 0x14000
	global_load_lds_dwordx4 v128, s[84:85]
	s_mov_b32 m0, s95
	s_add_i32 vcc_lo, s94, 0x16000
	global_load_lds_dwordx4 v168, s[28:29]
	s_mov_b32 m0, vcc_lo
	v_mov_b32_e32 v129, v169
	global_load_lds_dwordx4 v128, s[28:29]
	v_readlane_b32 s28, v254, 50
	v_readlane_b32 s29, v254, 51
	s_add_u32 s86, s28, s26
	s_addc_u32 s87, s29, s27
	s_add_i32 vcc_hi, s94, 0x2000
	s_mov_b32 m0, s94
	s_add_u32 s26, s86, 0x40000
	global_load_lds_dwordx4 v168, s[86:87]
	s_mov_b32 m0, vcc_hi
	s_addc_u32 s27, s87, 0
	s_add_i32 s28, s94, 0x4000
	global_load_lds_dwordx4 v128, s[86:87]
	s_mov_b32 m0, s28
	s_add_i32 s29, s94, 0x6000
	global_load_lds_dwordx4 v168, s[26:27]
	s_mov_b32 m0, s29
	s_cmp_eq_u32 s93, 1
	global_load_lds_dwordx4 v128, s[26:27]
	s_cselect_b64 s[26:27], -1, 0
	v_writelane_b32 v255, s26, 20
	s_mov_b64 s[44:45], s[52:53]
	s_mov_b64 s[54:55], s[48:49]
	s_mov_b64 s[52:53], s[42:43]
	v_lshl_add_u64 v[6:7], s[84:85], 0, v[168:169]
	v_lshl_add_u64 v[4:5], s[84:85], 0, v[128:129]
	v_lshl_add_u64 v[0:1], s[86:87], 0, v[168:169]
	v_writelane_b32 v255, s27, 21
	s_cmp_lg_u32 s93, 1
	v_lshl_add_u64 v[2:3], s[86:87], 0, v[128:129]
	s_cbranch_scc1 .LBB0_23
	s_barrier

.LBB0_31:
	s_or_b64 exec, exec, s[14:15]
	v_cmp_gt_i32_e32 vcc, s64, v118
	s_and_saveexec_b64 s[14:15], vcc
	s_cbranch_execz .LBB0_33
	v_add3_u32 v114, v118, s58, 33
	v_cmp_gt_i32_e32 vcc, s33, v114
	ds_read_b128 v[122:125], v120 offset:33280
	ds_read_b128 v[130:133], v120 offset:33296
	ds_read_b128 v[136:139], v119 offset:34320
	ds_read_b128 v[140:143], v119 offset:34336
	ds_read_b128 v[144:147], v119 offset:35360
	ds_read_b128 v[148:151], v119 offset:35376
	ds_read_b128 v[152:155], v119 offset:34832
	ds_read_b128 v[156:159], v119 offset:34848
	v_cndmask_b32_e32 v115, v178, v179, vcc
	v_and_b32_e32 v115, v115, v114
	v_cndmask_b32_e32 v135, v175, v176, vcc
	v_cmp_ne_u32_e32 vcc, 0, v115
	v_add_u32_e32 v115, 1, v115
	s_mov_b32 s24, 0xc0135761
	s_waitcnt lgkmcnt(6)
	v_cndmask_b32_e32 v121, 0, v133, vcc
	v_cndmask_b32_e32 v120, 0, v132, vcc
	v_cndmask_b32_e32 v127, 0, v131, vcc
	v_cndmask_b32_e32 v126, 0, v130, vcc
	v_cndmask_b32_e32 v125, 0, v125, vcc
	v_cndmask_b32_e32 v124, 0, v124, vcc
	v_cndmask_b32_e32 v123, 0, v123, vcc
	v_cndmask_b32_e32 v122, 0, v122, vcc
	v_cmp_lt_u32_e32 vcc, v115, v135
	v_ashrrev_i32_e32 v115, 31, v114
	v_lshlrev_b64 v[114:115], 13, v[114:115]
	s_waitcnt lgkmcnt(3)
	v_cndmask_b32_e32 v145, 0, v145, vcc
	v_cndmask_b32_e32 v144, 0, v144, vcc
	v_pk_fma_f32 v[144:145], v[104:105], v[144:145], v[108:109]
	s_waitcnt lgkmcnt(2)
	v_cndmask_b32_e32 v131, 0, v151, vcc
	v_pk_fma_f32 v[136:137], v[100:101], v[136:137], v[144:145]
	v_mov_b64_e32 v[144:145], s[24:25]
	v_pk_fma_f32 v[122:123], v[96:97], v[122:123], v[136:137]
	s_mov_b32 s24, 0x3dd2d3e8
	v_pk_mul_f32 v[136:137], v[122:123], v[122:123]
	v_cndmask_b32_e32 v130, 0, v150, vcc
	v_pk_fma_f32 v[136:137], v[136:137], s[24:25], v[144:145] op_sel_hi:[1,0,0] neg_lo:[1,0,0] neg_hi:[1,0,0]
	v_cndmask_b32_e32 v133, 0, v149, vcc
	v_pk_mul_f32 v[136:137], v[122:123], v[136:137]
	v_cndmask_b32_e32 v132, 0, v148, vcc
	v_exp_f32_e32 v136, v136
	v_exp_f32_e32 v137, v137
	v_cndmask_b32_e32 v147, 0, v147, vcc
	v_cndmask_b32_e32 v146, 0, v146, vcc
	v_pk_fma_f32 v[132:133], v[88:89], v[132:133], v[92:93]
	v_pk_add_f32 v[136:137], v[136:137], 1.0 op_sel_hi:[1,0]
	v_pk_fma_f32 v[130:131], v[90:91], v[130:131], v[94:95]
	v_rcp_f32_e32 v136, v136
	v_rcp_f32_e32 v137, v137
	v_pk_fma_f32 v[132:133], v[84:85], v[140:141], v[132:133]
	v_pk_fma_f32 v[130:131], v[86:87], v[142:143], v[130:131]
	v_pk_fma_f32 v[126:127], v[80:81], v[126:127], v[132:133]
	v_pk_mul_f32 v[122:123], v[122:123], v[136:137]
	v_pk_fma_f32 v[136:137], v[106:107], v[146:147], v[110:111]
	v_pk_fma_f32 v[120:121], v[82:83], v[120:121], v[130:131]
	v_pk_fma_f32 v[136:137], v[102:103], v[138:139], v[136:137]
	v_pk_mul_f32 v[132:133], v[126:127], v[126:127]
	v_pk_fma_f32 v[124:125], v[98:99], v[124:125], v[136:137]
	v_pk_mul_f32 v[130:131], v[120:121], v[120:121]
	v_pk_mul_f32 v[136:137], v[124:125], v[124:125]
	v_pk_fma_f32 v[132:133], v[132:133], s[24:25], v[144:145] op_sel_hi:[1,0,0] neg_lo:[1,0,0] neg_hi:[1,0,0]
	v_pk_fma_f32 v[136:137], v[136:137], s[24:25], v[144:145] op_sel_hi:[1,0,0] neg_lo:[1,0,0] neg_hi:[1,0,0]
	v_pk_fma_f32 v[130:131], v[130:131], s[24:25], v[144:145] op_sel_hi:[1,0,0] neg_lo:[1,0,0] neg_hi:[1,0,0]
	v_pk_mul_f32 v[136:137], v[124:125], v[136:137]
	v_pk_mul_f32 v[132:133], v[126:127], v[132:133]
	v_pk_mul_f32 v[130:131], v[120:121], v[130:131]
	v_exp_f32_e32 v136, v136
	v_exp_f32_e32 v137, v137
	v_exp_f32_e32 v132, v132
	v_exp_f32_e32 v133, v133
	v_exp_f32_e32 v130, v130
	v_exp_f32_e32 v131, v131
	v_pk_add_f32 v[136:137], v[136:137], 1.0 op_sel_hi:[1,0]
	v_pk_add_f32 v[132:133], v[132:133], 1.0 op_sel_hi:[1,0]
	v_rcp_f32_e32 v136, v136
	v_pk_add_f32 v[130:131], v[130:131], 1.0 op_sel_hi:[1,0]
	v_rcp_f32_e32 v137, v137
	v_rcp_f32_e32 v132, v132
	v_rcp_f32_e32 v133, v133
	v_rcp_f32_e32 v130, v130
	v_rcp_f32_e32 v131, v131
	v_pk_mul_f32 v[124:125], v[124:125], v[136:137]
	v_pk_mul_f32 v[126:127], v[126:127], v[132:133]
	s_waitcnt lgkmcnt(1)
	v_pk_mul_f32 v[122:123], v[152:153], v[122:123]
	v_pk_mul_f32 v[120:121], v[120:121], v[130:131]
	v_pk_mul_f32 v[124:125], v[154:155], v[124:125]
	s_waitcnt lgkmcnt(0)
	v_pk_mul_f32 v[126:127], v[156:157], v[126:127]
	v_pk_mul_f32 v[130:131], v[158:159], v[120:121]
	v_lshl_add_u64 v[114:115], s[46:47], 0, v[114:115]
	v_cvt_pk_bf16_f32 v120, v122, v123
	v_cvt_pk_bf16_f32 v121, v124, v125
	v_cvt_pk_bf16_f32 v122, v126, v127
	v_cvt_pk_bf16_f32 v123, v130, v131
	v_lshl_add_u64 v[114:115], v[112:113], 1, v[114:115]
	global_store_dwordx4 v[114:115], v[120:123], off
.LBB0_33:
	s_or_b64 exec, exec, s[14:15]
	v_cmp_gt_i32_e32 vcc, 63, v118
	v_add_u32_e32 v119, s58, v118
	s_and_saveexec_b64 s[14:15], vcc
	s_cbranch_execz .LBB0_35
	v_add_u32_e32 v120, 0x10400, v117
	v_add_u32_e32 v144, v116, v120
	v_add_u32_e32 v114, 0x41, v119
	ds_read_b128 v[120:123], v144
	ds_read_b128 v[124:127], v144 offset:16
	v_cmp_gt_i32_e32 vcc, s33, v114
	s_mov_b32 s5, 0x10810
	v_add3_u32 v152, v117, v116, s5
	v_cndmask_b32_e32 v115, v178, v179, vcc
	v_and_b32_e32 v115, v115, v114
	v_cndmask_b32_e32 v135, v175, v176, vcc
	ds_read_b128 v[130:133], v152
	ds_read_b128 v[136:139], v152 offset:16
	ds_read_b128 v[140:143], v144 offset:2080
	ds_read_b128 v[144:147], v144 offset:2096
	ds_read_b128 v[148:151], v152 offset:512
	ds_read_b128 v[152:155], v152 offset:528
	v_cmp_ne_u32_e32 vcc, 0, v115
	v_add_u32_e32 v115, 1, v115
	s_mov_b32 s24, 0xc0135761
	s_waitcnt lgkmcnt(6)
	v_cndmask_b32_e32 v127, 0, v127, vcc
	v_cndmask_b32_e32 v126, 0, v126, vcc
	v_cndmask_b32_e32 v125, 0, v125, vcc
	v_cndmask_b32_e32 v124, 0, v124, vcc
	v_cndmask_b32_e32 v123, 0, v123, vcc
	v_cndmask_b32_e32 v122, 0, v122, vcc
	v_cndmask_b32_e32 v121, 0, v121, vcc
	v_cndmask_b32_e32 v120, 0, v120, vcc
	v_cmp_lt_u32_e32 vcc, v115, v135
	v_ashrrev_i32_e32 v115, 31, v114
	v_lshlrev_b64 v[114:115], 13, v[114:115]
	s_waitcnt lgkmcnt(3)
	v_cndmask_b32_e32 v141, 0, v141, vcc
	v_cndmask_b32_e32 v140, 0, v140, vcc
	v_pk_fma_f32 v[140:141], v[104:105], v[140:141], v[108:109]
	v_cndmask_b32_e32 v143, 0, v143, vcc
	v_pk_fma_f32 v[130:131], v[100:101], v[130:131], v[140:141]
	v_mov_b64_e32 v[140:141], s[24:25]
	v_pk_fma_f32 v[120:121], v[96:97], v[120:121], v[130:131]
	s_mov_b32 s24, 0x3dd2d3e8
	v_pk_mul_f32 v[130:131], v[120:121], v[120:121]
	v_cndmask_b32_e32 v142, 0, v142, vcc
	v_pk_fma_f32 v[130:131], v[130:131], s[24:25], v[140:141] op_sel_hi:[1,0,0] neg_lo:[1,0,0] neg_hi:[1,0,0]
	s_waitcnt lgkmcnt(2)
	v_cndmask_b32_e32 v145, 0, v145, vcc
	v_pk_mul_f32 v[130:131], v[120:121], v[130:131]
	v_cndmask_b32_e32 v144, 0, v144, vcc
	v_exp_f32_e32 v130, v130
	v_exp_f32_e32 v131, v131
	v_cndmask_b32_e32 v147, 0, v147, vcc
	v_cndmask_b32_e32 v146, 0, v146, vcc
	v_lshl_add_u64 v[114:115], s[46:47], 0, v[114:115]
	v_pk_add_f32 v[130:131], v[130:131], 1.0 op_sel_hi:[1,0]
	v_lshl_add_u64 v[114:115], v[112:113], 1, v[114:115]
	v_rcp_f32_e32 v130, v130
	v_rcp_f32_e32 v131, v131
	s_nop 0
	v_pk_mul_f32 v[120:121], v[120:121], v[130:131]
	v_pk_fma_f32 v[130:131], v[106:107], v[142:143], v[110:111]
	s_waitcnt lgkmcnt(1)
	v_pk_mul_f32 v[120:121], v[148:149], v[120:121]
	v_pk_fma_f32 v[130:131], v[102:103], v[132:133], v[130:131]
	v_cvt_pk_bf16_f32 v120, v120, v121
	v_pk_fma_f32 v[122:123], v[98:99], v[122:123], v[130:131]
	s_nop 0
	v_pk_mul_f32 v[130:131], v[122:123], v[122:123]
	s_nop 0
	v_pk_fma_f32 v[130:131], v[130:131], s[24:25], v[140:141] op_sel_hi:[1,0,0] neg_lo:[1,0,0] neg_hi:[1,0,0]
	s_nop 0
	v_pk_mul_f32 v[130:131], v[122:123], v[130:131]
	s_nop 0
	v_exp_f32_e32 v130, v130
	v_exp_f32_e32 v131, v131
	s_nop 0
	v_pk_add_f32 v[130:131], v[130:131], 1.0 op_sel_hi:[1,0]
	s_nop 0
	v_rcp_f32_e32 v130, v130
	v_rcp_f32_e32 v131, v131
	s_nop 0
	v_pk_mul_f32 v[122:123], v[122:123], v[130:131]
	v_pk_fma_f32 v[130:131], v[88:89], v[144:145], v[92:93]
	v_pk_mul_f32 v[122:123], v[150:151], v[122:123]
	v_pk_fma_f32 v[130:131], v[84:85], v[136:137], v[130:131]
	v_cvt_pk_bf16_f32 v121, v122, v123
	v_pk_fma_f32 v[124:125], v[80:81], v[124:125], v[130:131]
	s_nop 0
	v_pk_mul_f32 v[130:131], v[124:125], v[124:125]
	s_nop 0
	v_pk_fma_f32 v[130:131], v[130:131], s[24:25], v[140:141] op_sel_hi:[1,0,0] neg_lo:[1,0,0] neg_hi:[1,0,0]
	s_nop 0
	v_pk_mul_f32 v[130:131], v[124:125], v[130:131]
	s_nop 0
	v_exp_f32_e32 v130, v130
	v_exp_f32_e32 v131, v131
	s_nop 0
	v_pk_add_f32 v[130:131], v[130:131], 1.0 op_sel_hi:[1,0]
	s_nop 0
	v_rcp_f32_e32 v130, v130
	v_rcp_f32_e32 v131, v131
	s_nop 0
	v_pk_mul_f32 v[124:125], v[124:125], v[130:131]
	v_pk_fma_f32 v[130:131], v[90:91], v[146:147], v[94:95]
	s_waitcnt lgkmcnt(0)
	v_pk_mul_f32 v[124:125], v[152:153], v[124:125]
	v_pk_fma_f32 v[130:131], v[86:87], v[138:139], v[130:131]
	v_cvt_pk_bf16_f32 v122, v124, v125
	v_pk_fma_f32 v[126:127], v[82:83], v[126:127], v[130:131]
	s_nop 0
	v_pk_mul_f32 v[130:131], v[126:127], v[126:127]
	s_nop 0
	v_pk_fma_f32 v[130:131], v[130:131], s[24:25], v[140:141] op_sel_hi:[1,0,0] neg_lo:[1,0,0] neg_hi:[1,0,0]
	s_nop 0
	v_pk_mul_f32 v[130:131], v[126:127], v[130:131]
	s_nop 0
	v_exp_f32_e32 v130, v130
	v_exp_f32_e32 v131, v131
	s_nop 0
	v_pk_add_f32 v[130:131], v[130:131], 1.0 op_sel_hi:[1,0]
	s_nop 0
	v_rcp_f32_e32 v130, v130
	v_rcp_f32_e32 v131, v131
	s_nop 0
	v_pk_mul_f32 v[126:127], v[126:127], v[130:131]
	s_nop 0
	v_pk_mul_f32 v[126:127], v[154:155], v[126:127]
	s_nop 0
	v_cvt_pk_bf16_f32 v123, v126, v127
	global_store_dwordx4 v[114:115], v[120:123], off
.LBB0_35:
	s_or_b64 exec, exec, s[14:15]
	v_cmp_gt_i32_e32 vcc, 31, v118
	s_and_saveexec_b64 s[14:15], vcc
	s_cbranch_execz .LBB0_37
	v_add_u32_e32 v118, 0x18600, v117
	v_add_u32_e32 v127, v116, v118
	v_add_u32_e32 v114, 0x61, v119
	ds_read_b128 v[118:121], v127
	ds_read_b128 v[122:125], v127 offset:16
	v_cmp_gt_i32_e32 vcc, s33, v114
	s_mov_b32 s5, 0x18a10
	v_add3_u32 v116, v117, v116, s5
	v_cndmask_b32_e32 v115, v178, v179, vcc
	v_and_b32_e32 v115, v115, v114
	ds_read_b128 v[130:133], v116
	ds_read_b128 v[136:139], v116 offset:16
	ds_read_b128 v[140:143], v127 offset:2080
	ds_read_b128 v[144:147], v127 offset:2096
	ds_read_b128 v[148:151], v116 offset:512
	ds_read_b128 v[152:155], v116 offset:528
	v_cndmask_b32_e32 v126, v175, v176, vcc
	v_cmp_ne_u32_e32 vcc, 0, v115
	v_add_u32_e32 v115, 1, v115
	s_mov_b32 s24, 0xc0135761
	s_waitcnt lgkmcnt(6)
	v_cndmask_b32_e32 v117, 0, v125, vcc
	v_cndmask_b32_e32 v116, 0, v124, vcc
	v_cndmask_b32_e32 v123, 0, v123, vcc
	v_cndmask_b32_e32 v122, 0, v122, vcc
	v_cndmask_b32_e32 v121, 0, v121, vcc
	v_cndmask_b32_e32 v120, 0, v120, vcc
	v_cndmask_b32_e32 v119, 0, v119, vcc
	v_cndmask_b32_e32 v118, 0, v118, vcc
	v_cmp_lt_u32_e32 vcc, v115, v126
	v_ashrrev_i32_e32 v115, 31, v114
	s_waitcnt lgkmcnt(2)
	v_cndmask_b32_e32 v127, 0, v145, vcc
	v_cndmask_b32_e32 v126, 0, v144, vcc
	v_cndmask_b32_e32 v141, 0, v141, vcc
	v_cndmask_b32_e32 v140, 0, v140, vcc
	v_pk_fma_f32 v[88:89], v[88:89], v[126:127], v[92:93]
	v_pk_fma_f32 v[104:105], v[104:105], v[140:141], v[108:109]
	v_pk_fma_f32 v[84:85], v[84:85], v[136:137], v[88:89]
	v_pk_fma_f32 v[100:101], v[100:101], v[130:131], v[104:105]
	v_pk_fma_f32 v[80:81], v[80:81], v[122:123], v[84:85]
	v_pk_fma_f32 v[96:97], v[96:97], v[118:119], v[100:101]
	v_mov_b64_e32 v[104:105], s[24:25]
	s_mov_b32 s24, 0x3dd2d3e8
	v_pk_mul_f32 v[84:85], v[80:81], v[80:81]
	v_pk_mul_f32 v[100:101], v[96:97], v[96:97]
	v_pk_fma_f32 v[84:85], v[84:85], s[24:25], v[104:105] op_sel_hi:[1,0,0] neg_lo:[1,0,0] neg_hi:[1,0,0]
	v_pk_fma_f32 v[100:101], v[100:101], s[24:25], v[104:105] op_sel_hi:[1,0,0] neg_lo:[1,0,0] neg_hi:[1,0,0]
	v_pk_mul_f32 v[84:85], v[80:81], v[84:85]
	v_pk_mul_f32 v[100:101], v[96:97], v[100:101]
	v_exp_f32_e32 v84, v84
	v_exp_f32_e32 v85, v85
	v_exp_f32_e32 v100, v100
	v_exp_f32_e32 v101, v101
	v_cndmask_b32_e32 v125, 0, v147, vcc
	v_pk_add_f32 v[84:85], v[84:85], 1.0 op_sel_hi:[1,0]
	v_cndmask_b32_e32 v124, 0, v146, vcc
	v_pk_add_f32 v[100:101], v[100:101], 1.0 op_sel_hi:[1,0]
	v_rcp_f32_e32 v84, v84
	v_rcp_f32_e32 v85, v85
	v_rcp_f32_e32 v100, v100
	v_rcp_f32_e32 v101, v101
	v_cndmask_b32_e32 v143, 0, v143, vcc
	v_cndmask_b32_e32 v142, 0, v142, vcc
	v_pk_mul_f32 v[80:81], v[80:81], v[84:85]
	v_pk_mul_f32 v[96:97], v[96:97], v[100:101]
	v_pk_fma_f32 v[100:101], v[106:107], v[142:143], v[110:111]
	s_waitcnt lgkmcnt(0)
	v_pk_mul_f32 v[84:85], v[152:153], v[80:81]
	v_pk_fma_f32 v[80:81], v[90:91], v[124:125], v[94:95]
	v_pk_fma_f32 v[100:101], v[102:103], v[132:133], v[100:101]
	v_pk_fma_f32 v[80:81], v[86:87], v[138:139], v[80:81]
	v_pk_fma_f32 v[98:99], v[98:99], v[120:121], v[100:101]
	v_pk_fma_f32 v[80:81], v[82:83], v[116:117], v[80:81]
	v_pk_mul_f32 v[100:101], v[98:99], v[98:99]
	v_pk_mul_f32 v[82:83], v[80:81], v[80:81]
	v_pk_fma_f32 v[100:101], v[100:101], s[24:25], v[104:105] op_sel_hi:[1,0,0] neg_lo:[1,0,0] neg_hi:[1,0,0]
	v_pk_fma_f32 v[82:83], v[82:83], s[24:25], v[104:105] op_sel_hi:[1,0,0] neg_lo:[1,0,0] neg_hi:[1,0,0]
	v_pk_mul_f32 v[100:101], v[98:99], v[100:101]
	v_pk_mul_f32 v[82:83], v[80:81], v[82:83]
	v_exp_f32_e32 v100, v100
	v_exp_f32_e32 v101, v101
	v_exp_f32_e32 v82, v82
	v_exp_f32_e32 v83, v83
	v_pk_mul_f32 v[96:97], v[148:149], v[96:97]
	v_pk_add_f32 v[100:101], v[100:101], 1.0 op_sel_hi:[1,0]
	v_pk_add_f32 v[82:83], v[82:83], 1.0 op_sel_hi:[1,0]
	v_rcp_f32_e32 v100, v100
	v_rcp_f32_e32 v101, v101
	v_rcp_f32_e32 v82, v82
	v_rcp_f32_e32 v83, v83
	v_pk_mul_f32 v[98:99], v[98:99], v[100:101]
	s_nop 0
	v_pk_mul_f32 v[98:99], v[150:151], v[98:99]
	v_pk_mul_f32 v[80:81], v[80:81], v[82:83]
	v_cvt_pk_bf16_f32 v82, v84, v85
	v_lshlrev_b64 v[84:85], 13, v[114:115]
	v_pk_mul_f32 v[86:87], v[154:155], v[80:81]
	v_lshl_add_u64 v[84:85], s[46:47], 0, v[84:85]
	v_cvt_pk_bf16_f32 v80, v96, v97
	v_cvt_pk_bf16_f32 v81, v98, v99
	v_cvt_pk_bf16_f32 v83, v86, v87
	v_lshl_add_u64 v[84:85], v[112:113], 1, v[84:85]
	global_store_dwordx4 v[84:85], v[80:83], off

.LBB0_41:
	s_or_b64 exec, exec, s[14:15]
	s_add_i32 s5, s91, 0x9f
	v_add_u32_e32 v34, s5, v39
	s_mov_b32 s5, 0x14000
	v_cmp_gt_i32_e32 vcc, s64, v39
	v_cmp_gt_i32_e64 s[40:41], s5, v34
	s_and_b64 s[26:27], vcc, s[40:41]
	s_and_saveexec_b64 s[14:15], s[26:27]
	s_cbranch_execz .LBB0_43
	v_add_u32_e32 v48, 0x8200, v38
	v_add_u32_e32 v44, v37, v48
	ds_read_b128 v[40:43], v44
	ds_read_b128 v[44:47], v44 offset:16
	v_cmp_gt_i32_e32 vcc, s33, v34
	v_lshl_add_u32 v68, v36, 2, v48
	ds_read_b128 v[48:51], v68 offset:1040
	ds_read_b128 v[52:55], v68 offset:1056
	ds_read_b128 v[56:59], v68 offset:2080
	ds_read_b128 v[60:63], v68 offset:2096
	ds_read_b128 v[64:67], v68 offset:1552
	ds_read_b128 v[68:71], v68 offset:1568
	v_cndmask_b32_e32 v35, v178, v179, vcc
	v_and_b32_e32 v35, v35, v34
	v_cndmask_b32_e32 v72, v175, v176, vcc
	v_cmp_ne_u32_e32 vcc, 0, v35
	v_add_u32_e32 v35, 1, v35
	s_mov_b32 s24, 0xc0135761
	s_waitcnt lgkmcnt(6)
	v_cndmask_b32_e32 v47, 0, v47, vcc
	v_cndmask_b32_e32 v46, 0, v46, vcc
	v_cndmask_b32_e32 v45, 0, v45, vcc
	v_cndmask_b32_e32 v44, 0, v44, vcc
	v_cndmask_b32_e32 v43, 0, v43, vcc
	v_cndmask_b32_e32 v42, 0, v42, vcc
	v_cndmask_b32_e32 v41, 0, v41, vcc
	v_cndmask_b32_e32 v40, 0, v40, vcc
	v_cmp_lt_u32_e32 vcc, v35, v72
	v_ashrrev_i32_e32 v35, 31, v34
	v_lshlrev_b64 v[34:35], 13, v[34:35]
	s_waitcnt lgkmcnt(3)
	v_cndmask_b32_e32 v57, 0, v57, vcc
	v_cndmask_b32_e32 v56, 0, v56, vcc
	v_pk_fma_f32 v[56:57], v[24:25], v[56:57], v[28:29]
	v_cndmask_b32_e32 v59, 0, v59, vcc
	v_pk_fma_f32 v[48:49], v[20:21], v[48:49], v[56:57]
	v_mov_b64_e32 v[56:57], s[24:25]
	v_pk_fma_f32 v[40:41], v[16:17], v[40:41], v[48:49]
	s_mov_b32 s24, 0x3dd2d3e8
	v_pk_mul_f32 v[48:49], v[40:41], v[40:41]
	v_cndmask_b32_e32 v58, 0, v58, vcc
	v_pk_fma_f32 v[48:49], v[48:49], s[24:25], v[56:57] op_sel_hi:[1,0,0] neg_lo:[1,0,0] neg_hi:[1,0,0]
	s_waitcnt lgkmcnt(2)
	v_cndmask_b32_e32 v61, 0, v61, vcc
	v_pk_mul_f32 v[48:49], v[40:41], v[48:49]
	v_cndmask_b32_e32 v60, 0, v60, vcc
	v_exp_f32_e32 v48, v48
	v_exp_f32_e32 v49, v49
	v_cndmask_b32_e32 v63, 0, v63, vcc
	v_cndmask_b32_e32 v62, 0, v62, vcc
	v_lshl_add_u64 v[34:35], s[46:47], 0, v[34:35]
	v_pk_add_f32 v[48:49], v[48:49], 1.0 op_sel_hi:[1,0]
	v_lshl_add_u64 v[34:35], v[32:33], 1, v[34:35]
	v_rcp_f32_e32 v48, v48
	v_rcp_f32_e32 v49, v49
	s_nop 0
	v_pk_mul_f32 v[40:41], v[40:41], v[48:49]
	v_pk_fma_f32 v[48:49], v[26:27], v[58:59], v[30:31]
	s_waitcnt lgkmcnt(1)
	v_pk_mul_f32 v[40:41], v[64:65], v[40:41]
	v_pk_fma_f32 v[48:49], v[22:23], v[50:51], v[48:49]
	v_cvt_pk_bf16_f32 v40, v40, v41
	v_pk_fma_f32 v[42:43], v[18:19], v[42:43], v[48:49]
	s_nop 0
	v_pk_mul_f32 v[48:49], v[42:43], v[42:43]
	s_nop 0
	v_pk_fma_f32 v[48:49], v[48:49], s[24:25], v[56:57] op_sel_hi:[1,0,0] neg_lo:[1,0,0] neg_hi:[1,0,0]
	s_nop 0
	v_pk_mul_f32 v[48:49], v[42:43], v[48:49]
	s_nop 0
	v_exp_f32_e32 v48, v48
	v_exp_f32_e32 v49, v49
	s_nop 0
	v_pk_add_f32 v[48:49], v[48:49], 1.0 op_sel_hi:[1,0]
	s_nop 0
	v_rcp_f32_e32 v48, v48
	v_rcp_f32_e32 v49, v49
	s_nop 0
	v_pk_mul_f32 v[42:43], v[42:43], v[48:49]
	v_pk_fma_f32 v[48:49], v[8:9], v[60:61], v[12:13]
	v_pk_mul_f32 v[42:43], v[66:67], v[42:43]
	v_pk_fma_f32 v[48:49], v[4:5], v[52:53], v[48:49]
	v_cvt_pk_bf16_f32 v41, v42, v43
	v_pk_fma_f32 v[44:45], v[0:1], v[44:45], v[48:49]
	s_nop 0
	v_pk_mul_f32 v[48:49], v[44:45], v[44:45]
	s_nop 0
	v_pk_fma_f32 v[48:49], v[48:49], s[24:25], v[56:57] op_sel_hi:[1,0,0] neg_lo:[1,0,0] neg_hi:[1,0,0]
	s_nop 0
	v_pk_mul_f32 v[48:49], v[44:45], v[48:49]
	s_nop 0
	v_exp_f32_e32 v48, v48
	v_exp_f32_e32 v49, v49
	s_nop 0
	v_pk_add_f32 v[48:49], v[48:49], 1.0 op_sel_hi:[1,0]
	s_nop 0
	v_rcp_f32_e32 v48, v48
	v_rcp_f32_e32 v49, v49
	s_nop 0
	v_pk_mul_f32 v[44:45], v[44:45], v[48:49]
	v_pk_fma_f32 v[48:49], v[10:11], v[62:63], v[14:15]
	s_waitcnt lgkmcnt(0)
	v_pk_mul_f32 v[44:45], v[68:69], v[44:45]
	v_pk_fma_f32 v[48:49], v[6:7], v[54:55], v[48:49]
	v_cvt_pk_bf16_f32 v42, v44, v45
	v_pk_fma_f32 v[46:47], v[2:3], v[46:47], v[48:49]
	s_nop 0
	v_pk_mul_f32 v[48:49], v[46:47], v[46:47]
	s_nop 0
	v_pk_fma_f32 v[48:49], v[48:49], s[24:25], v[56:57] op_sel_hi:[1,0,0] neg_lo:[1,0,0] neg_hi:[1,0,0]
	s_nop 0
	v_pk_mul_f32 v[48:49], v[46:47], v[48:49]
	s_nop 0
	v_exp_f32_e32 v48, v48
	v_exp_f32_e32 v49, v49
	s_nop 0
	v_pk_add_f32 v[48:49], v[48:49], 1.0 op_sel_hi:[1,0]
	s_nop 0
	v_rcp_f32_e32 v48, v48
	v_rcp_f32_e32 v49, v49
	s_nop 0
	v_pk_mul_f32 v[46:47], v[46:47], v[48:49]
	s_nop 0
	v_pk_mul_f32 v[46:47], v[70:71], v[46:47]
	s_nop 0
	v_cvt_pk_bf16_f32 v43, v46, v47
	global_store_dwordx4 v[34:35], v[40:43], off
.LBB0_43:
	s_or_b64 exec, exec, s[14:15]
	s_add_i32 s5, s91, 0xbf
	v_add_u32_e32 v34, s5, v39
	s_mov_b32 s5, 0x14000
	v_cmp_gt_i32_e32 vcc, 63, v39
	v_cmp_gt_i32_e64 s[40:41], s5, v34
	s_and_b64 s[26:27], vcc, s[40:41]
	s_and_saveexec_b64 s[14:15], s[26:27]
	s_cbranch_execz .LBB0_45
	v_add_u32_e32 v48, 0x10400, v38
	v_add_u32_e32 v44, v37, v48
	ds_read_b128 v[40:43], v44
	ds_read_b128 v[44:47], v44 offset:16
	v_cmp_gt_i32_e32 vcc, s33, v34
	v_lshl_add_u32 v68, v36, 2, v48
	ds_read_b128 v[48:51], v68 offset:1040
	ds_read_b128 v[52:55], v68 offset:1056
	ds_read_b128 v[56:59], v68 offset:2080
	ds_read_b128 v[60:63], v68 offset:2096
	ds_read_b128 v[64:67], v68 offset:1552
	ds_read_b128 v[68:71], v68 offset:1568
	v_cndmask_b32_e32 v35, v178, v179, vcc
	v_and_b32_e32 v35, v35, v34
	v_cndmask_b32_e32 v72, v175, v176, vcc
	v_cmp_ne_u32_e32 vcc, 0, v35
	v_add_u32_e32 v35, 1, v35
	s_mov_b32 s24, 0xc0135761
	s_waitcnt lgkmcnt(6)
	v_cndmask_b32_e32 v47, 0, v47, vcc
	v_cndmask_b32_e32 v46, 0, v46, vcc
	v_cndmask_b32_e32 v45, 0, v45, vcc
	v_cndmask_b32_e32 v44, 0, v44, vcc
	v_cndmask_b32_e32 v43, 0, v43, vcc
	v_cndmask_b32_e32 v42, 0, v42, vcc
	v_cndmask_b32_e32 v41, 0, v41, vcc
	v_cndmask_b32_e32 v40, 0, v40, vcc
	v_cmp_lt_u32_e32 vcc, v35, v72
	v_ashrrev_i32_e32 v35, 31, v34
	v_lshlrev_b64 v[34:35], 13, v[34:35]
	s_waitcnt lgkmcnt(3)
	v_cndmask_b32_e32 v57, 0, v57, vcc
	v_cndmask_b32_e32 v56, 0, v56, vcc
	v_pk_fma_f32 v[56:57], v[24:25], v[56:57], v[28:29]
	v_cndmask_b32_e32 v59, 0, v59, vcc
	v_pk_fma_f32 v[48:49], v[20:21], v[48:49], v[56:57]
	v_mov_b64_e32 v[56:57], s[24:25]
	v_pk_fma_f32 v[40:41], v[16:17], v[40:41], v[48:49]
	s_mov_b32 s24, 0x3dd2d3e8
	v_pk_mul_f32 v[48:49], v[40:41], v[40:41]
	v_cndmask_b32_e32 v58, 0, v58, vcc
	v_pk_fma_f32 v[48:49], v[48:49], s[24:25], v[56:57] op_sel_hi:[1,0,0] neg_lo:[1,0,0] neg_hi:[1,0,0]
	s_waitcnt lgkmcnt(2)
	v_cndmask_b32_e32 v61, 0, v61, vcc
	v_pk_mul_f32 v[48:49], v[40:41], v[48:49]
	v_cndmask_b32_e32 v60, 0, v60, vcc
	v_exp_f32_e32 v48, v48
	v_exp_f32_e32 v49, v49
	v_cndmask_b32_e32 v63, 0, v63, vcc
	v_cndmask_b32_e32 v62, 0, v62, vcc
	v_lshl_add_u64 v[34:35], s[46:47], 0, v[34:35]
	v_pk_add_f32 v[48:49], v[48:49], 1.0 op_sel_hi:[1,0]
	v_lshl_add_u64 v[34:35], v[32:33], 1, v[34:35]
	v_rcp_f32_e32 v48, v48
	v_rcp_f32_e32 v49, v49
	s_nop 0
	v_pk_mul_f32 v[40:41], v[40:41], v[48:49]
	v_pk_fma_f32 v[48:49], v[26:27], v[58:59], v[30:31]
	s_waitcnt lgkmcnt(1)
	v_pk_mul_f32 v[40:41], v[64:65], v[40:41]
	v_pk_fma_f32 v[48:49], v[22:23], v[50:51], v[48:49]
	v_cvt_pk_bf16_f32 v40, v40, v41
	v_pk_fma_f32 v[42:43], v[18:19], v[42:43], v[48:49]
	s_nop 0
	v_pk_mul_f32 v[48:49], v[42:43], v[42:43]
	s_nop 0
	v_pk_fma_f32 v[48:49], v[48:49], s[24:25], v[56:57] op_sel_hi:[1,0,0] neg_lo:[1,0,0] neg_hi:[1,0,0]
	s_nop 0
	v_pk_mul_f32 v[48:49], v[42:43], v[48:49]
	s_nop 0
	v_exp_f32_e32 v48, v48
	v_exp_f32_e32 v49, v49
	s_nop 0
	v_pk_add_f32 v[48:49], v[48:49], 1.0 op_sel_hi:[1,0]
	s_nop 0
	v_rcp_f32_e32 v48, v48
	v_rcp_f32_e32 v49, v49
	s_nop 0
	v_pk_mul_f32 v[42:43], v[42:43], v[48:49]
	v_pk_fma_f32 v[48:49], v[8:9], v[60:61], v[12:13]
	v_pk_mul_f32 v[42:43], v[66:67], v[42:43]
	v_pk_fma_f32 v[48:49], v[4:5], v[52:53], v[48:49]
	v_cvt_pk_bf16_f32 v41, v42, v43
	v_pk_fma_f32 v[44:45], v[0:1], v[44:45], v[48:49]
	s_nop 0
	v_pk_mul_f32 v[48:49], v[44:45], v[44:45]
	s_nop 0
	v_pk_fma_f32 v[48:49], v[48:49], s[24:25], v[56:57] op_sel_hi:[1,0,0] neg_lo:[1,0,0] neg_hi:[1,0,0]
	s_nop 0
	v_pk_mul_f32 v[48:49], v[44:45], v[48:49]
	s_nop 0
	v_exp_f32_e32 v48, v48
	v_exp_f32_e32 v49, v49
	s_nop 0
	v_pk_add_f32 v[48:49], v[48:49], 1.0 op_sel_hi:[1,0]
	s_nop 0
	v_rcp_f32_e32 v48, v48
	v_rcp_f32_e32 v49, v49
	s_nop 0
	v_pk_mul_f32 v[44:45], v[44:45], v[48:49]
	v_pk_fma_f32 v[48:49], v[10:11], v[62:63], v[14:15]
	s_waitcnt lgkmcnt(0)
	v_pk_mul_f32 v[44:45], v[68:69], v[44:45]
	v_pk_fma_f32 v[48:49], v[6:7], v[54:55], v[48:49]
	v_cvt_pk_bf16_f32 v42, v44, v45
	v_pk_fma_f32 v[46:47], v[2:3], v[46:47], v[48:49]
	s_nop 0
	v_pk_mul_f32 v[48:49], v[46:47], v[46:47]
	s_nop 0
	v_pk_fma_f32 v[48:49], v[48:49], s[24:25], v[56:57] op_sel_hi:[1,0,0] neg_lo:[1,0,0] neg_hi:[1,0,0]
	s_nop 0
	v_pk_mul_f32 v[48:49], v[46:47], v[48:49]
	s_nop 0
	v_exp_f32_e32 v48, v48
	v_exp_f32_e32 v49, v49
	s_nop 0
	v_pk_add_f32 v[48:49], v[48:49], 1.0 op_sel_hi:[1,0]
	s_nop 0
	v_rcp_f32_e32 v48, v48
	v_rcp_f32_e32 v49, v49
	s_nop 0
	v_pk_mul_f32 v[46:47], v[46:47], v[48:49]
	s_nop 0
	v_pk_mul_f32 v[46:47], v[70:71], v[46:47]
	s_nop 0
	v_cvt_pk_bf16_f32 v43, v46, v47
	global_store_dwordx4 v[34:35], v[40:43], off
.LBB0_45:
	s_or_b64 exec, exec, s[14:15]
	s_addk_i32 s91, 0xdf
	v_add_u32_e32 v34, s91, v39
	v_cmp_gt_i32_e32 vcc, 31, v39
	v_cmp_gt_i32_e64 s[40:41], s5, v34
	s_and_b64 s[26:27], vcc, s[40:41]
	s_and_saveexec_b64 s[14:15], s[26:27]
	s_cbranch_execz .LBB0_18
	v_add_u32_e32 v46, 0x18600, v38
	v_add_u32_e32 v37, v37, v46
	ds_read_b128 v[38:41], v37
	ds_read_b128 v[42:45], v37 offset:16
	v_cmp_gt_i32_e32 vcc, s33, v34
	v_lshl_add_u32 v36, v36, 2, v46
	ds_read_b128 v[46:49], v36 offset:1040
	ds_read_b128 v[50:53], v36 offset:1056
	ds_read_b128 v[54:57], v36 offset:2080
	ds_read_b128 v[58:61], v36 offset:2096
	ds_read_b128 v[62:65], v36 offset:1552
	ds_read_b128 v[66:69], v36 offset:1568
	v_cndmask_b32_e32 v35, v178, v179, vcc
	v_and_b32_e32 v35, v35, v34
	v_cndmask_b32_e32 v70, v175, v176, vcc
	v_cmp_ne_u32_e32 vcc, 0, v35
	v_add_u32_e32 v35, 1, v35
	s_mov_b32 s24, 0xc0135761
	s_waitcnt lgkmcnt(6)
	v_cndmask_b32_e32 v37, 0, v45, vcc
	v_cndmask_b32_e32 v36, 0, v44, vcc
	v_cndmask_b32_e32 v43, 0, v43, vcc
	v_cndmask_b32_e32 v42, 0, v42, vcc
	v_cndmask_b32_e32 v41, 0, v41, vcc
	v_cndmask_b32_e32 v40, 0, v40, vcc
	v_cndmask_b32_e32 v39, 0, v39, vcc
	v_cndmask_b32_e32 v38, 0, v38, vcc
	v_cmp_lt_u32_e32 vcc, v35, v70
	v_ashrrev_i32_e32 v35, 31, v34
	s_waitcnt lgkmcnt(2)
	v_cndmask_b32_e32 v59, 0, v59, vcc
	v_cndmask_b32_e32 v58, 0, v58, vcc
	v_cndmask_b32_e32 v55, 0, v55, vcc
	v_cndmask_b32_e32 v54, 0, v54, vcc
	v_pk_fma_f32 v[8:9], v[8:9], v[58:59], v[12:13]
	v_pk_fma_f32 v[24:25], v[24:25], v[54:55], v[28:29]
	v_pk_fma_f32 v[4:5], v[4:5], v[50:51], v[8:9]
	v_pk_fma_f32 v[20:21], v[20:21], v[46:47], v[24:25]
	v_pk_fma_f32 v[0:1], v[0:1], v[42:43], v[4:5]
	v_pk_fma_f32 v[16:17], v[16:17], v[38:39], v[20:21]
	v_mov_b64_e32 v[24:25], s[24:25]
	s_mov_b32 s24, 0x3dd2d3e8
	v_pk_mul_f32 v[4:5], v[0:1], v[0:1]
	v_pk_mul_f32 v[20:21], v[16:17], v[16:17]
	v_pk_fma_f32 v[4:5], v[4:5], s[24:25], v[24:25] op_sel_hi:[1,0,0] neg_lo:[1,0,0] neg_hi:[1,0,0]
	v_pk_fma_f32 v[20:21], v[20:21], s[24:25], v[24:25] op_sel_hi:[1,0,0] neg_lo:[1,0,0] neg_hi:[1,0,0]
	v_pk_mul_f32 v[4:5], v[0:1], v[4:5]
	v_pk_mul_f32 v[20:21], v[16:17], v[20:21]
	v_exp_f32_e32 v4, v4
	v_exp_f32_e32 v5, v5
	v_exp_f32_e32 v20, v20
	v_exp_f32_e32 v21, v21
	v_cndmask_b32_e32 v45, 0, v61, vcc
	v_pk_add_f32 v[4:5], v[4:5], 1.0 op_sel_hi:[1,0]
	v_cndmask_b32_e32 v44, 0, v60, vcc
	v_pk_add_f32 v[20:21], v[20:21], 1.0 op_sel_hi:[1,0]
	v_rcp_f32_e32 v4, v4
	v_rcp_f32_e32 v5, v5
	v_rcp_f32_e32 v20, v20
	v_rcp_f32_e32 v21, v21
	v_cndmask_b32_e32 v57, 0, v57, vcc
	v_cndmask_b32_e32 v56, 0, v56, vcc
	v_pk_mul_f32 v[0:1], v[0:1], v[4:5]
	v_pk_mul_f32 v[16:17], v[16:17], v[20:21]
	v_pk_fma_f32 v[20:21], v[26:27], v[56:57], v[30:31]
	s_waitcnt lgkmcnt(0)
	v_pk_mul_f32 v[4:5], v[66:67], v[0:1]
	v_pk_fma_f32 v[0:1], v[10:11], v[44:45], v[14:15]
	v_pk_fma_f32 v[20:21], v[22:23], v[48:49], v[20:21]
	v_pk_fma_f32 v[0:1], v[6:7], v[52:53], v[0:1]
	v_pk_fma_f32 v[18:19], v[18:19], v[40:41], v[20:21]
	v_pk_fma_f32 v[0:1], v[2:3], v[36:37], v[0:1]
	v_pk_mul_f32 v[20:21], v[18:19], v[18:19]
	v_pk_mul_f32 v[2:3], v[0:1], v[0:1]
	v_pk_fma_f32 v[20:21], v[20:21], s[24:25], v[24:25] op_sel_hi:[1,0,0] neg_lo:[1,0,0] neg_hi:[1,0,0]
	v_pk_fma_f32 v[2:3], v[2:3], s[24:25], v[24:25] op_sel_hi:[1,0,0] neg_lo:[1,0,0] neg_hi:[1,0,0]
	v_pk_mul_f32 v[20:21], v[18:19], v[20:21]
	v_pk_mul_f32 v[2:3], v[0:1], v[2:3]
	v_exp_f32_e32 v20, v20
	v_exp_f32_e32 v21, v21
	v_exp_f32_e32 v2, v2
	v_exp_f32_e32 v3, v3
	v_pk_mul_f32 v[16:17], v[62:63], v[16:17]
	v_pk_add_f32 v[20:21], v[20:21], 1.0 op_sel_hi:[1,0]
	v_pk_add_f32 v[2:3], v[2:3], 1.0 op_sel_hi:[1,0]
	v_rcp_f32_e32 v20, v20
	v_rcp_f32_e32 v21, v21
	v_rcp_f32_e32 v2, v2
	v_rcp_f32_e32 v3, v3
	v_pk_mul_f32 v[18:19], v[18:19], v[20:21]
	s_nop 0
	v_pk_mul_f32 v[18:19], v[64:65], v[18:19]
	v_pk_mul_f32 v[0:1], v[0:1], v[2:3]
	v_cvt_pk_bf16_f32 v2, v4, v5
	v_lshlrev_b64 v[4:5], 13, v[34:35]
	v_pk_mul_f32 v[6:7], v[68:69], v[0:1]
	v_lshl_add_u64 v[4:5], s[46:47], 0, v[4:5]
	v_cvt_pk_bf16_f32 v0, v16, v17
	v_cvt_pk_bf16_f32 v1, v18, v19
	v_cvt_pk_bf16_f32 v3, v6, v7
	v_lshl_add_u64 v[4:5], v[32:33], 1, v[4:5]
	global_store_dwordx4 v[4:5], v[0:3], off
	s_branch .LBB0_18
.Lp4_skip_b0:
	s_waitcnt vmcnt(0)
	s_branch .LBB0_41
